# P5/P6 K-loop: LDS-DMA stage issue interleaved into MFMA blocks, recounted vmcnt
# baseline (speedup 1.0000x reference)
; #define PG8_LDA(dst, b, h) do { if constexpr (FP8) { _Pragma("unroll") for (int m = 0; m < 4; ++m) dst##8[m] = PG8_LD8(PG8_SA(b, h), aoff, aoff1, m); } \
;         else { _Pragma("unroll") for (int m = 0; m < 4; ++m) _Pragma("unroll") for (int k = 0; k < 2; ++k) dst[m][k] = *(const LAS bf16x8*)(lds + PG8_SA(b, h) + (k ? aoff1 : aoff) + m * 2048); } } while (0)
; #define PG8_LDB(dst, b, h) do { if constexpr (FP8) { dst##8[0] = PG8_LD8(PG8_SB(b, h), boff, boff1, 0); dst##8[1] = PG8_LD8(PG8_SB(b, h), boff, boff1, 1); } \
;         else { _Pragma("unroll") for (int n = 0; n < 2; ++n) _Pragma("unroll") for (int k = 0; k < 2; ++k) dst[n][k] = *(const LAS bf16x8*)(lds + PG8_SB(b, h) + (k ? boff1 : boff) + n * 2048); } } while (0)
; #define PG8_WAIT_V(n) asm volatile("s_waitcnt vmcnt(" #n ")" ::: "memory")
; #define PG8_WAIT_L(n) asm volatile("s_waitcnt lgkmcnt(" #n ")" ::: "memory")
; #define PG8_BAR __builtin_amdgcn_s_barrier()
; #define PG8_SCHED __builtin_amdgcn_sched_barrier(0)
; #define PG8_S1 PG8_STAGE(PG8_SA(1, 1), a1 + hstepA, voffA)
; #define PG8_S2 do { PG8_STAGE(PG8_SB(0, 0), b2, voffB); PG8_STAGE(PG8_SB(0, 1), b2 + hstepB, voffB); PG8_STAGE(PG8_SA(0, 0), a2, voffA); } while (0)
; template <class Epi, class SchedT, bool ALIGN_EPI, bool SP2, bool FP8 = false>
; __device__ __forceinline__ void gemm_phase(LAS unsigned char* lds, const Gemm g, const SchedT& S, const Epi& E, const int wid) {
;     ...
;             const bool last = (t == nt - 2);
;             const char* a1 = cA + (size_t)(t + 1) * kstep;
;             const char* a2 = last ? nA : cA + (size_t)(t + 2) * kstep; const char* b2 = last ? nB : cB + (size_t)(t + 2) * kstep;
;             const char* a3 = a2 + kstep; const char* b3 = b2 + kstep;
;             if constexpr (SP2) {
;     ...
;             PG8_LDB(B0, 0, 0); PG8_LDB(B1, 0, 1); PG8_SCHED; PG8_LDA(At, 0, 0); PG8_S1;
;             PG8_WAIT_V(8); PG8_WAIT_L(0); PG8_BAR; PG8_MMAP(0, 0, 0); PG8_BAR; PG8_SCHED;
;             PG8_LDA(At, 0, 1); PG8_S2;
;             PG8_WAIT_V(8); PG8_WAIT_L(0); PG8_BAR; PG8_MMAP(1, 0, 1); PG8_BAR; PG8_SCHED;
.LBB0_899:
	ds_read_b128 v[128:131], v173
	ds_read_b128 v[132:135], v173 offset:1024
	ds_read_b128 v[136:139], v174
	ds_read_b128 v[140:143], v174 offset:1024
	ds_read_b128 v[150:153], v175
	ds_read_b128 v[154:157], v175 offset:1024
	ds_read_b128 v[158:161], v176
	ds_read_b128 v[162:165], v176 offset:1024
	s_add_i32 s35, s34, 2
	s_add_u32 s16, s48, 0xfffc0080
	s_addc_u32 s17, s49, -1
	s_cmp_eq_u32 s27, s34
	s_cselect_b32 s51, s15, s17
	s_cselect_b32 s50, s21, s16
	s_cselect_b32 s53, s24, s31
	s_cselect_b32 s52, s25, s30
	v_mov_b32_e32 v144, v168
	ds_read_b128 v[182:185], v177
	ds_read_b128 v[186:189], v177 offset:1024
	ds_read_b128 v[190:193], v177 offset:2048
	ds_read_b128 v[194:197], v177 offset:3072
	ds_read_b128 v[198:201], v177 offset:4096
	ds_read_b128 v[202:205], v177 offset:5120
	ds_read_b128 v[206:209], v177 offset:6144
	ds_read_b128 v[210:213], v177 offset:7168
	s_waitcnt vmcnt(6)
	s_waitcnt lgkmcnt(0)
	s_barrier
	s_setprio 1
	s_waitcnt lgkmcnt(0)
	v_mfma_f32_16x16x32_bf16 v[124:127], v[128:131], v[182:185], v[124:127]
	v_mfma_f32_16x16x32_bf16 v[120:123], v[136:139], v[182:185], v[120:123]
	v_mfma_f32_16x16x32_bf16 v[108:111], v[128:131], v[190:193], v[108:111]
	v_mfma_f32_16x16x32_bf16 v[104:107], v[136:139], v[190:193], v[104:107]
	v_mfma_f32_16x16x32_bf16 v[92:95], v[128:131], v[198:201], v[92:95]
	v_mfma_f32_16x16x32_bf16 v[88:91], v[136:139], v[198:201], v[88:91]
	v_mfma_f32_16x16x32_bf16 v[76:79], v[128:131], v[206:209], v[76:79]
	v_mfma_f32_16x16x32_bf16 v[72:75], v[136:139], v[206:209], v[72:75]
	v_mfma_f32_16x16x32_bf16 v[124:127], v[132:135], v[186:189], v[124:127]
	v_mfma_f32_16x16x32_bf16 v[120:123], v[140:143], v[186:189], v[120:123]
	s_add_i32 m0, s87, 0xc000
	s_nop 0
	global_load_lds_dwordx4 v144, s[48:49]
	v_mfma_f32_16x16x32_bf16 v[108:111], v[132:135], v[194:197], v[108:111]
	v_mfma_f32_16x16x32_bf16 v[104:107], v[140:143], v[194:197], v[104:107]
	v_mfma_f32_16x16x32_bf16 v[92:95], v[132:135], v[202:205], v[92:95]
	v_mfma_f32_16x16x32_bf16 v[88:91], v[140:143], v[202:205], v[88:91]
	v_mfma_f32_16x16x32_bf16 v[76:79], v[132:135], v[210:213], v[76:79]
	v_mfma_f32_16x16x32_bf16 v[72:75], v[140:143], v[210:213], v[72:75]
	s_setprio 0
	s_setprio 1
	v_mfma_f32_16x16x32_bf16 v[116:119], v[150:153], v[182:185], v[116:119]
	v_mfma_f32_16x16x32_bf16 v[112:115], v[158:161], v[182:185], v[112:115]
	v_mfma_f32_16x16x32_bf16 v[100:103], v[150:153], v[190:193], v[100:103]
	v_mfma_f32_16x16x32_bf16 v[96:99], v[158:161], v[190:193], v[96:99]
	v_mfma_f32_16x16x32_bf16 v[84:87], v[150:153], v[198:201], v[84:87]
	v_mov_b32_e32 v144, v170
	s_add_i32 m0, s87, 0xe000
	s_nop 0
	global_load_lds_dwordx4 v144, s[48:49]
	v_mfma_f32_16x16x32_bf16 v[80:83], v[158:161], v[198:201], v[80:83]
	v_mfma_f32_16x16x32_bf16 v[68:71], v[150:153], v[206:209], v[68:71]
	v_mfma_f32_16x16x32_bf16 v[64:67], v[158:161], v[206:209], v[64:67]
	v_mfma_f32_16x16x32_bf16 v[116:119], v[154:157], v[186:189], v[116:119]
	v_mfma_f32_16x16x32_bf16 v[112:115], v[162:165], v[186:189], v[112:115]
	v_mfma_f32_16x16x32_bf16 v[100:103], v[154:157], v[194:197], v[100:103]
	v_mfma_f32_16x16x32_bf16 v[96:99], v[162:165], v[194:197], v[96:99]
	v_mfma_f32_16x16x32_bf16 v[84:87], v[154:157], v[202:205], v[84:87]
	v_mfma_f32_16x16x32_bf16 v[80:83], v[162:165], v[202:205], v[80:83]
	v_mfma_f32_16x16x32_bf16 v[68:71], v[154:157], v[210:213], v[68:71]
	v_mfma_f32_16x16x32_bf16 v[64:67], v[162:165], v[210:213], v[64:67]
	s_setprio 0
	s_barrier
	v_mov_b32_e32 v144, v169
	s_add_i32 s16, s94, s86
	ds_read_b128 v[182:185], v177 offset:16384
	ds_read_b128 v[186:189], v177 offset:17408
	ds_read_b128 v[190:193], v177 offset:18432
	ds_read_b128 v[194:197], v177 offset:19456
	ds_read_b128 v[198:201], v177 offset:20480
	ds_read_b128 v[202:205], v177 offset:21504
	ds_read_b128 v[206:209], v177 offset:22528
	ds_read_b128 v[210:213], v177 offset:23552
	s_waitcnt vmcnt(2)
	s_waitcnt lgkmcnt(0)
	s_barrier
	s_setprio 1
	s_waitcnt lgkmcnt(0)
	v_mfma_f32_16x16x32_bf16 v[60:63], v[128:131], v[182:185], v[60:63]
	v_mfma_f32_16x16x32_bf16 v[56:59], v[136:139], v[182:185], v[56:59]
	v_mfma_f32_16x16x32_bf16 v[44:47], v[128:131], v[190:193], v[44:47]
	v_mfma_f32_16x16x32_bf16 v[40:43], v[136:139], v[190:193], v[40:43]
	s_mov_b32 m0, s16
	s_nop 0
	global_load_lds_dwordx4 v144, s[52:53]
	v_mfma_f32_16x16x32_bf16 v[28:31], v[128:131], v[198:201], v[28:31]
	v_mfma_f32_16x16x32_bf16 v[24:27], v[136:139], v[198:201], v[24:27]
	v_mfma_f32_16x16x32_bf16 v[12:15], v[128:131], v[206:209], v[12:15]
	v_mfma_f32_16x16x32_bf16 v[8:11], v[136:139], v[206:209], v[8:11]
	v_mfma_f32_16x16x32_bf16 v[60:63], v[132:135], v[186:189], v[60:63]
	v_mov_b32_e32 v144, v171
	s_add_i32 m0, s16, 0x2000
	s_add_u32 s60, s52, 0x40000
	global_load_lds_dwordx4 v144, s[52:53]
	v_mfma_f32_16x16x32_bf16 v[56:59], v[140:143], v[186:189], v[56:59]
	v_mfma_f32_16x16x32_bf16 v[44:47], v[132:135], v[194:197], v[44:47]
	v_mfma_f32_16x16x32_bf16 v[40:43], v[140:143], v[194:197], v[40:43]
	v_mfma_f32_16x16x32_bf16 v[28:31], v[132:135], v[202:205], v[28:31]
	s_addc_u32 s61, s53, 0
	v_mov_b32_e32 v144, v169
	s_add_i32 s16, s95, s86
	s_mov_b32 m0, s16
	s_nop 0
	global_load_lds_dwordx4 v144, s[60:61]
	v_mfma_f32_16x16x32_bf16 v[24:27], v[140:143], v[202:205], v[24:27]
	v_mfma_f32_16x16x32_bf16 v[12:15], v[132:135], v[210:213], v[12:15]
	v_mfma_f32_16x16x32_bf16 v[8:11], v[140:143], v[210:213], v[8:11]
	s_setprio 0
	s_setprio 1
	v_mfma_f32_16x16x32_bf16 v[52:55], v[150:153], v[182:185], v[52:55]
	v_mfma_f32_16x16x32_bf16 v[48:51], v[158:161], v[182:185], v[48:51]
	v_mov_b32_e32 v144, v171
	s_add_i32 m0, s16, 0x2000
	s_nop 0
	global_load_lds_dwordx4 v144, s[60:61]
	v_mfma_f32_16x16x32_bf16 v[36:39], v[150:153], v[190:193], v[36:39]
	v_mfma_f32_16x16x32_bf16 v[32:35], v[158:161], v[190:193], v[32:35]
	v_mfma_f32_16x16x32_bf16 v[20:23], v[150:153], v[198:201], v[20:23]
	v_mfma_f32_16x16x32_bf16 v[16:19], v[158:161], v[198:201], v[16:19]
	v_mov_b32_e32 v144, v168
	s_mov_b32 m0, s87
	s_nop 0
	global_load_lds_dwordx4 v144, s[50:51]
	v_mfma_f32_16x16x32_bf16 v[4:7], v[150:153], v[206:209], v[4:7]
	v_mfma_f32_16x16x32_bf16 v[0:3], v[158:161], v[206:209], v[0:3]
	v_mfma_f32_16x16x32_bf16 v[52:55], v[154:157], v[186:189], v[52:55]
	v_mfma_f32_16x16x32_bf16 v[48:51], v[162:165], v[186:189], v[48:51]
	v_mfma_f32_16x16x32_bf16 v[36:39], v[154:157], v[194:197], v[36:39]
	v_mov_b32_e32 v144, v170
	s_mov_b32 m0, s88
	s_nop 0
	global_load_lds_dwordx4 v144, s[50:51]
	v_mfma_f32_16x16x32_bf16 v[32:35], v[162:165], v[194:197], v[32:35]
	v_mfma_f32_16x16x32_bf16 v[20:23], v[154:157], v[202:205], v[20:23]
	v_mfma_f32_16x16x32_bf16 v[16:19], v[162:165], v[202:205], v[16:19]
	v_mfma_f32_16x16x32_bf16 v[4:7], v[154:157], v[210:213], v[4:7]
	v_mfma_f32_16x16x32_bf16 v[0:3], v[162:165], v[210:213], v[0:3]
	s_setprio 0
	s_barrier
; #define PG8_LDA(dst, b, h) do { if constexpr (FP8) { _Pragma("unroll") for (int m = 0; m < 4; ++m) dst##8[m] = PG8_LD8(PG8_SA(b, h), aoff, aoff1, m); } \
;         else { _Pragma("unroll") for (int m = 0; m < 4; ++m) _Pragma("unroll") for (int k = 0; k < 2; ++k) dst[m][k] = *(const LAS bf16x8*)(lds + PG8_SA(b, h) + (k ? aoff1 : aoff) + m * 2048); } } while (0)
; #define PG8_LDB(dst, b, h) do { if constexpr (FP8) { dst##8[0] = PG8_LD8(PG8_SB(b, h), boff, boff1, 0); dst##8[1] = PG8_LD8(PG8_SB(b, h), boff, boff1, 1); } \
;         else { _Pragma("unroll") for (int n = 0; n < 2; ++n) _Pragma("unroll") for (int k = 0; k < 2; ++k) dst[n][k] = *(const LAS bf16x8*)(lds + PG8_SB(b, h) + (k ? boff1 : boff) + n * 2048); } } while (0)
; #define PG8_WAIT_V(n) asm volatile("s_waitcnt vmcnt(" #n ")" ::: "memory")
; #define PG8_WAIT_L(n) asm volatile("s_waitcnt lgkmcnt(" #n ")" ::: "memory")
; #define PG8_BAR __builtin_amdgcn_s_barrier()
; #define PG8_SCHED __builtin_amdgcn_sched_barrier(0)
; #define PG8_S3 PG8_STAGE(PG8_SA(0, 1), a2 + hstepA, voffA)
; #define PG8_S4 do { PG8_STAGE(PG8_SB(1, 0), b3, voffB); PG8_STAGE(PG8_SB(1, 1), b3 + hstepB, voffB); PG8_STAGE(PG8_SA(1, 0), a3, voffA); } while (0)
; template <class Epi, class SchedT, bool ALIGN_EPI, bool SP2, bool FP8 = false>
; __device__ __forceinline__ void gemm_phase(LAS unsigned char* lds, const Gemm g, const SchedT& S, const Epi& E, const int wid) {
;     ...
;             PG8_LDB(B0, 1, 0); PG8_LDB(B1, 1, 1); PG8_SCHED; PG8_LDA(At, 1, 0); PG8_S3;
;             PG8_WAIT_V(8); PG8_WAIT_L(0); PG8_BAR; PG8_MMAP(0, 1, 0); PG8_BAR; PG8_SCHED;
;             PG8_LDA(At, 1, 1); PG8_S4;
;             PG8_WAIT_V(8); PG8_WAIT_L(0); PG8_BAR; PG8_MMAP(1, 1, 1); PG8_BAR; PG8_SCHED;
	s_add_i32 s16, 0, 0x18000
	s_add_i32 s17, 0, 0x1c000
	v_add_u32_e32 v132, s16, v172
	v_add_u32_e32 v144, s17, v172
	ds_read_b128 v[128:131], v132
	ds_read_b128 v[132:135], v132 offset:1024
	ds_read_b128 v[136:139], v178
	ds_read_b128 v[140:143], v178 offset:1024
	ds_read_b128 v[150:153], v144
	ds_read_b128 v[154:157], v144 offset:1024
	ds_read_b128 v[158:161], v179
	ds_read_b128 v[162:165], v179 offset:1024
	s_add_u32 s60, s50, 0x40000
	v_mov_b32_e32 v144, v168
	s_mov_b32 m0, s89
	ds_read_b128 v[182:185], v177 offset:32768
	ds_read_b128 v[186:189], v177 offset:33792
	ds_read_b128 v[190:193], v177 offset:34816
	ds_read_b128 v[194:197], v177 offset:35840
	ds_read_b128 v[198:201], v177 offset:36864
	ds_read_b128 v[202:205], v177 offset:37888
	ds_read_b128 v[206:209], v177 offset:38912
	ds_read_b128 v[210:213], v177 offset:39936
	s_waitcnt vmcnt(6)
	s_waitcnt lgkmcnt(0)
	s_barrier
	s_setprio 1
	s_waitcnt lgkmcnt(0)
	v_mfma_f32_16x16x32_bf16 v[124:127], v[128:131], v[182:185], v[124:127]
	v_mfma_f32_16x16x32_bf16 v[120:123], v[136:139], v[182:185], v[120:123]
	v_mfma_f32_16x16x32_bf16 v[108:111], v[128:131], v[190:193], v[108:111]
	v_mfma_f32_16x16x32_bf16 v[104:107], v[136:139], v[190:193], v[104:107]
	v_mfma_f32_16x16x32_bf16 v[92:95], v[128:131], v[198:201], v[92:95]
	v_mfma_f32_16x16x32_bf16 v[88:91], v[136:139], v[198:201], v[88:91]
	v_mfma_f32_16x16x32_bf16 v[76:79], v[128:131], v[206:209], v[76:79]
	v_mfma_f32_16x16x32_bf16 v[72:75], v[136:139], v[206:209], v[72:75]
	v_mfma_f32_16x16x32_bf16 v[124:127], v[132:135], v[186:189], v[124:127]
	v_mfma_f32_16x16x32_bf16 v[120:123], v[140:143], v[186:189], v[120:123]
	s_addc_u32 s61, s51, 0
	s_nop 0
	global_load_lds_dwordx4 v144, s[60:61]
	v_mfma_f32_16x16x32_bf16 v[108:111], v[132:135], v[194:197], v[108:111]
	v_mfma_f32_16x16x32_bf16 v[104:107], v[140:143], v[194:197], v[104:107]
	v_mfma_f32_16x16x32_bf16 v[92:95], v[132:135], v[202:205], v[92:95]
	v_mfma_f32_16x16x32_bf16 v[88:91], v[140:143], v[202:205], v[88:91]
	v_mfma_f32_16x16x32_bf16 v[76:79], v[132:135], v[210:213], v[76:79]
	v_mfma_f32_16x16x32_bf16 v[72:75], v[140:143], v[210:213], v[72:75]
	s_setprio 0
	s_setprio 1
	v_mfma_f32_16x16x32_bf16 v[116:119], v[150:153], v[182:185], v[116:119]
	v_mfma_f32_16x16x32_bf16 v[112:115], v[158:161], v[182:185], v[112:115]
	v_mfma_f32_16x16x32_bf16 v[100:103], v[150:153], v[190:193], v[100:103]
	v_mfma_f32_16x16x32_bf16 v[96:99], v[158:161], v[190:193], v[96:99]
	v_mfma_f32_16x16x32_bf16 v[84:87], v[150:153], v[198:201], v[84:87]
	v_mov_b32_e32 v144, v170
	s_mov_b32 m0, s90
	s_nop 0
	global_load_lds_dwordx4 v144, s[60:61]
	v_mfma_f32_16x16x32_bf16 v[80:83], v[158:161], v[198:201], v[80:83]
	v_mfma_f32_16x16x32_bf16 v[68:71], v[150:153], v[206:209], v[68:71]
	v_mfma_f32_16x16x32_bf16 v[64:67], v[158:161], v[206:209], v[64:67]
	v_mfma_f32_16x16x32_bf16 v[116:119], v[154:157], v[186:189], v[116:119]
	v_mfma_f32_16x16x32_bf16 v[112:115], v[162:165], v[186:189], v[112:115]
	v_mfma_f32_16x16x32_bf16 v[100:103], v[154:157], v[194:197], v[100:103]
	v_mfma_f32_16x16x32_bf16 v[96:99], v[162:165], v[194:197], v[96:99]
	v_mfma_f32_16x16x32_bf16 v[84:87], v[154:157], v[202:205], v[84:87]
	v_mfma_f32_16x16x32_bf16 v[80:83], v[162:165], v[202:205], v[80:83]
	v_mfma_f32_16x16x32_bf16 v[68:71], v[154:157], v[210:213], v[68:71]
	v_mfma_f32_16x16x32_bf16 v[64:67], v[162:165], v[210:213], v[64:67]
	s_setprio 0
	s_barrier
	v_mov_b32_e32 v144, v169
	ds_read_b128 v[182:185], v177 offset:49152
	ds_read_b128 v[186:189], v177 offset:50176
	ds_read_b128 v[190:193], v177 offset:51200
	ds_read_b128 v[194:197], v177 offset:52224
	ds_read_b128 v[198:201], v177 offset:53248
	ds_read_b128 v[202:205], v177 offset:54272
	ds_read_b128 v[206:209], v177 offset:55296
	ds_read_b128 v[210:213], v177 offset:56320
	s_waitcnt vmcnt(2)
	s_waitcnt lgkmcnt(0)
	s_barrier
; #define PG8_LDA(dst, b, h) do { if constexpr (FP8) { _Pragma("unroll") for (int m = 0; m < 4; ++m) dst##8[m] = PG8_LD8(PG8_SA(b, h), aoff, aoff1, m); } \
;         else { _Pragma("unroll") for (int m = 0; m < 4; ++m) _Pragma("unroll") for (int k = 0; k < 2; ++k) dst[m][k] = *(const LAS bf16x8*)(lds + PG8_SA(b, h) + (k ? aoff1 : aoff) + m * 2048); } } while (0)
; #define PG8_LDB(dst, b, h) do { if constexpr (FP8) { dst##8[0] = PG8_LD8(PG8_SB(b, h), boff, boff1, 0); dst##8[1] = PG8_LD8(PG8_SB(b, h), boff, boff1, 1); } \
;         else { _Pragma("unroll") for (int n = 0; n < 2; ++n) _Pragma("unroll") for (int k = 0; k < 2; ++k) dst[n][k] = *(const LAS bf16x8*)(lds + PG8_SB(b, h) + (k ? boff1 : boff) + n * 2048); } } while (0)
; #define PG8_WAIT_V(n) asm volatile("s_waitcnt vmcnt(" #n ")" ::: "memory")
; #define PG8_WAIT_L(n) asm volatile("s_waitcnt lgkmcnt(" #n ")" ::: "memory")
; #define PG8_BAR __builtin_amdgcn_s_barrier()
; #define PG8_SCHED __builtin_amdgcn_sched_barrier(0)
; #define PG8_S3 PG8_STAGE(PG8_SA(0, 1), a2 + hstepA, voffA)
; #define PG8_S4 do { PG8_STAGE(PG8_SB(1, 0), b3, voffB); PG8_STAGE(PG8_SB(1, 1), b3 + hstepB, voffB); PG8_STAGE(PG8_SA(1, 0), a3, voffA); } while (0)
; template <class Epi, class SchedT, bool ALIGN_EPI, bool SP2, bool FP8 = false>
; __device__ __forceinline__ void gemm_phase(LAS unsigned char* lds, const Gemm g, const SchedT& S, const Epi& E, const int wid) {
;     ...
;             PG8_LDB(B0, 1, 0); PG8_LDB(B1, 1, 1); PG8_SCHED; PG8_LDA(At, 1, 0); PG8_S3;
;             PG8_WAIT_V(8); PG8_WAIT_L(0); PG8_BAR; PG8_MMAP(0, 1, 0); PG8_BAR; PG8_SCHED;
;             PG8_LDA(At, 1, 1); PG8_S4;
;             PG8_WAIT_V(8); PG8_WAIT_L(0); PG8_BAR; PG8_MMAP(1, 1, 1); PG8_BAR; PG8_SCHED;
	s_setprio 1
	s_waitcnt lgkmcnt(0)
	v_mfma_f32_16x16x32_bf16 v[60:63], v[128:131], v[182:185], v[60:63]
	v_mfma_f32_16x16x32_bf16 v[56:59], v[136:139], v[182:185], v[56:59]
	v_mfma_f32_16x16x32_bf16 v[44:47], v[128:131], v[190:193], v[44:47]
	v_mfma_f32_16x16x32_bf16 v[40:43], v[136:139], v[190:193], v[40:43]
	s_add_i32 s16, s16, s86
	v_lshl_add_u64 v[166:167], s[52:53], 0, v[144:145]
	v_lshl_add_u64 v[166:167], v[166:167], 0, s[6:7]
	s_mov_b32 m0, s16
	v_mov_b32_e32 v144, v171
	global_load_lds_dwordx4 v[166:167], off
	v_mfma_f32_16x16x32_bf16 v[28:31], v[128:131], v[198:201], v[28:31]
	v_mfma_f32_16x16x32_bf16 v[24:27], v[136:139], v[198:201], v[24:27]
	v_mfma_f32_16x16x32_bf16 v[12:15], v[128:131], v[206:209], v[12:15]
	v_mfma_f32_16x16x32_bf16 v[8:11], v[136:139], v[206:209], v[8:11]
	v_mfma_f32_16x16x32_bf16 v[60:63], v[132:135], v[186:189], v[60:63]
	s_add_i32 m0, s16, 0x2000
	s_nop 0
	v_lshl_add_u64 v[166:167], s[52:53], 0, v[144:145]
	s_add_u32 s52, s52, 0x40080
	v_lshl_add_u64 v[166:167], v[166:167], 0, s[6:7]
	s_addc_u32 s53, s53, 0
	v_mov_b32_e32 v144, v169
	s_add_i32 s16, s17, s86
	global_load_lds_dwordx4 v[166:167], off
	v_mfma_f32_16x16x32_bf16 v[56:59], v[140:143], v[186:189], v[56:59]
	v_mfma_f32_16x16x32_bf16 v[44:47], v[132:135], v[194:197], v[44:47]
	v_mfma_f32_16x16x32_bf16 v[40:43], v[140:143], v[194:197], v[40:43]
	v_mfma_f32_16x16x32_bf16 v[28:31], v[132:135], v[202:205], v[28:31]
	s_mov_b32 m0, s16
	s_nop 0
	global_load_lds_dwordx4 v144, s[52:53]
	v_mfma_f32_16x16x32_bf16 v[24:27], v[140:143], v[202:205], v[24:27]
	v_mfma_f32_16x16x32_bf16 v[12:15], v[132:135], v[210:213], v[12:15]
	v_mfma_f32_16x16x32_bf16 v[8:11], v[140:143], v[210:213], v[8:11]
	s_setprio 0
	s_setprio 1
	v_mfma_f32_16x16x32_bf16 v[52:55], v[150:153], v[182:185], v[52:55]
	v_mfma_f32_16x16x32_bf16 v[48:51], v[158:161], v[182:185], v[48:51]
	v_mov_b32_e32 v144, v171
	s_add_i32 m0, s16, 0x2000
	s_nop 0
	global_load_lds_dwordx4 v144, s[52:53]
	v_mfma_f32_16x16x32_bf16 v[36:39], v[150:153], v[190:193], v[36:39]
	v_mfma_f32_16x16x32_bf16 v[32:35], v[158:161], v[190:193], v[32:35]
	v_mfma_f32_16x16x32_bf16 v[20:23], v[150:153], v[198:201], v[20:23]
	v_mfma_f32_16x16x32_bf16 v[16:19], v[158:161], v[198:201], v[16:19]
	v_mov_b32_e32 v144, v168
	s_mov_b32 m0, s92
	v_lshl_add_u64 v[166:167], s[50:51], 0, v[144:145]
	v_lshl_add_u64 v[166:167], v[166:167], 0, s[6:7]
	v_mov_b32_e32 v144, v170
	global_load_lds_dwordx4 v[166:167], off
	v_mfma_f32_16x16x32_bf16 v[4:7], v[150:153], v[206:209], v[4:7]
	v_mfma_f32_16x16x32_bf16 v[0:3], v[158:161], v[206:209], v[0:3]
	v_mfma_f32_16x16x32_bf16 v[52:55], v[154:157], v[186:189], v[52:55]
	v_mfma_f32_16x16x32_bf16 v[48:51], v[162:165], v[186:189], v[48:51]
	v_mfma_f32_16x16x32_bf16 v[36:39], v[154:157], v[194:197], v[36:39]
	s_mov_b32 m0, s93
	v_lshl_add_u64 v[166:167], s[50:51], 0, v[144:145]
	v_lshl_add_u64 v[166:167], v[166:167], 0, s[6:7]
	global_load_lds_dwordx4 v[166:167], off
	v_mfma_f32_16x16x32_bf16 v[32:35], v[162:165], v[194:197], v[32:35]
	v_mfma_f32_16x16x32_bf16 v[20:23], v[154:157], v[202:205], v[20:23]
	v_mfma_f32_16x16x32_bf16 v[16:19], v[162:165], v[202:205], v[16:19]
	v_mfma_f32_16x16x32_bf16 v[4:7], v[154:157], v[210:213], v[4:7]
	v_mfma_f32_16x16x32_bf16 v[0:3], v[162:165], v[210:213], v[0:3]
	s_setprio 0
	s_barrier
	s_add_u32 s48, s48, 0x100
	s_addc_u32 s49, s49, 0
	s_add_u32 s30, s30, 0x100
	s_addc_u32 s31, s31, 0
	s_cmp_ge_i32 s35, s20
	s_mov_b32 s34, s35
	s_cbranch_scc0 .LBB0_899
	s_branch .LBB0_894

; #define PG8_LDA(dst, b, h) do { if constexpr (FP8) { _Pragma("unroll") for (int m = 0; m < 4; ++m) dst##8[m] = PG8_LD8(PG8_SA(b, h), aoff, aoff1, m); } \
;         else { _Pragma("unroll") for (int m = 0; m < 4; ++m) _Pragma("unroll") for (int k = 0; k < 2; ++k) dst[m][k] = *(const LAS bf16x8*)(lds + PG8_SA(b, h) + (k ? aoff1 : aoff) + m * 2048); } } while (0)
; #define PG8_LDB(dst, b, h) do { if constexpr (FP8) { dst##8[0] = PG8_LD8(PG8_SB(b, h), boff, boff1, 0); dst##8[1] = PG8_LD8(PG8_SB(b, h), boff, boff1, 1); } \
;         else { _Pragma("unroll") for (int n = 0; n < 2; ++n) _Pragma("unroll") for (int k = 0; k < 2; ++k) dst[n][k] = *(const LAS bf16x8*)(lds + PG8_SB(b, h) + (k ? boff1 : boff) + n * 2048); } } while (0)
; #define PG8_WAIT_V(n) asm volatile("s_waitcnt vmcnt(" #n ")" ::: "memory")
; #define PG8_WAIT_L(n) asm volatile("s_waitcnt lgkmcnt(" #n ")" ::: "memory")
; #define PG8_BAR __builtin_amdgcn_s_barrier()
; #define PG8_SCHED __builtin_amdgcn_sched_barrier(0)
; #define PG8_S1 PG8_STAGE(PG8_SA(1, 1), a1 + hstepA, voffA)
; #define PG8_S2 do { PG8_STAGE(PG8_SB(0, 0), b2, voffB); PG8_STAGE(PG8_SB(0, 1), b2 + hstepB, voffB); PG8_STAGE(PG8_SA(0, 0), a2, voffA); } while (0)
; template <class Epi, class SchedT, bool ALIGN_EPI, bool SP2, bool FP8 = false>
; __device__ __forceinline__ void gemm_phase(LAS unsigned char* lds, const Gemm g, const SchedT& S, const Epi& E, const int wid) {
;     ...
;             const bool last = (t == nt - 2);
;             const char* a1 = cA + (size_t)(t + 1) * kstep;
;             const char* a2 = last ? nA : cA + (size_t)(t + 2) * kstep; const char* b2 = last ? nB : cB + (size_t)(t + 2) * kstep;
;             const char* a3 = a2 + kstep; const char* b3 = b2 + kstep;
;             if constexpr (SP2) {
;     ...
;             PG8_LDB(B0, 0, 0); PG8_LDB(B1, 0, 1); PG8_SCHED; PG8_LDA(At, 0, 0); PG8_S1;
;             PG8_WAIT_V(8); PG8_WAIT_L(0); PG8_BAR; PG8_MMAP(0, 0, 0); PG8_BAR; PG8_SCHED;
;             PG8_LDA(At, 0, 1); PG8_S2;
;             PG8_WAIT_V(8); PG8_WAIT_L(0); PG8_BAR; PG8_MMAP(1, 0, 1); PG8_BAR; PG8_SCHED;
.LBB0_970:
	ds_read_b128 v[134:137], v175
	ds_read_b128 v[138:141], v175 offset:1024
	ds_read_b128 v[142:145], v176
	ds_read_b128 v[146:149], v176 offset:1024
	ds_read_b128 v[150:153], v177
	ds_read_b128 v[154:157], v177 offset:1024
	ds_read_b128 v[158:161], v178
	ds_read_b128 v[162:165], v178 offset:1024
	s_add_i32 s48, s34, 2
	s_add_u32 s16, s24, 0xfff00080
	s_addc_u32 s17, s25, -1
	s_cmp_eq_u32 s45, s34
	s_cselect_b32 s34, s15, s16
	s_cselect_b32 s35, s13, s17
	s_cselect_b32 s39, s27, s47
	s_cselect_b32 s38, s31, s46
	v_mov_b32_e32 v128, v172
	ds_read_b128 v[166:169], v179
	ds_read_b128 v[184:187], v179 offset:1024
	ds_read_b128 v[188:191], v179 offset:2048
	ds_read_b128 v[192:195], v179 offset:3072
	ds_read_b128 v[196:199], v179 offset:4096
	ds_read_b128 v[200:203], v179 offset:5120
	ds_read_b128 v[204:207], v179 offset:6144
	ds_read_b128 v[208:211], v179 offset:7168
	s_waitcnt vmcnt(6)
	s_waitcnt lgkmcnt(0)
	s_barrier
	s_setprio 1
	s_waitcnt lgkmcnt(0)
	v_mfma_f32_16x16x32_bf16 v[124:127], v[134:137], v[166:169], v[124:127]
	v_mfma_f32_16x16x32_bf16 v[120:123], v[142:145], v[166:169], v[120:123]
	v_mfma_f32_16x16x32_bf16 v[108:111], v[134:137], v[188:191], v[108:111]
	v_mfma_f32_16x16x32_bf16 v[104:107], v[142:145], v[188:191], v[104:107]
	v_mfma_f32_16x16x32_bf16 v[92:95], v[134:137], v[196:199], v[92:95]
	v_mfma_f32_16x16x32_bf16 v[88:91], v[142:145], v[196:199], v[88:91]
	v_mfma_f32_16x16x32_bf16 v[76:79], v[134:137], v[204:207], v[76:79]
	v_mfma_f32_16x16x32_bf16 v[72:75], v[142:145], v[204:207], v[72:75]
	v_mfma_f32_16x16x32_bf16 v[124:127], v[138:141], v[184:187], v[124:127]
	v_mfma_f32_16x16x32_bf16 v[120:123], v[146:149], v[184:187], v[120:123]
	s_add_i32 m0, s87, 0xc000
	s_nop 0
	global_load_lds_dwordx4 v128, s[24:25]
	v_mfma_f32_16x16x32_bf16 v[108:111], v[138:141], v[192:195], v[108:111]
	v_mfma_f32_16x16x32_bf16 v[104:107], v[146:149], v[192:195], v[104:107]
	v_mfma_f32_16x16x32_bf16 v[92:95], v[138:141], v[200:203], v[92:95]
	v_mfma_f32_16x16x32_bf16 v[88:91], v[146:149], v[200:203], v[88:91]
	v_mfma_f32_16x16x32_bf16 v[76:79], v[138:141], v[208:211], v[76:79]
	v_mfma_f32_16x16x32_bf16 v[72:75], v[146:149], v[208:211], v[72:75]
	s_setprio 0
	s_setprio 1
	v_mfma_f32_16x16x32_bf16 v[116:119], v[150:153], v[166:169], v[116:119]
	v_mfma_f32_16x16x32_bf16 v[112:115], v[158:161], v[166:169], v[112:115]
	v_mfma_f32_16x16x32_bf16 v[100:103], v[150:153], v[188:191], v[100:103]
	v_mfma_f32_16x16x32_bf16 v[96:99], v[158:161], v[188:191], v[96:99]
	v_mfma_f32_16x16x32_bf16 v[84:87], v[150:153], v[196:199], v[84:87]
	v_mov_b32_e32 v128, v173
	s_add_i32 m0, s87, 0xe000
	s_nop 0
	global_load_lds_dwordx4 v128, s[24:25]
	v_mfma_f32_16x16x32_bf16 v[80:83], v[158:161], v[196:199], v[80:83]
	v_mfma_f32_16x16x32_bf16 v[68:71], v[150:153], v[204:207], v[68:71]
	v_mfma_f32_16x16x32_bf16 v[64:67], v[158:161], v[204:207], v[64:67]
	v_mfma_f32_16x16x32_bf16 v[116:119], v[154:157], v[184:187], v[116:119]
	v_mfma_f32_16x16x32_bf16 v[112:115], v[162:165], v[184:187], v[112:115]
	v_mfma_f32_16x16x32_bf16 v[100:103], v[154:157], v[192:195], v[100:103]
	v_mfma_f32_16x16x32_bf16 v[96:99], v[162:165], v[192:195], v[96:99]
	v_mfma_f32_16x16x32_bf16 v[84:87], v[154:157], v[200:203], v[84:87]
	v_mfma_f32_16x16x32_bf16 v[80:83], v[162:165], v[200:203], v[80:83]
	v_mfma_f32_16x16x32_bf16 v[68:71], v[154:157], v[208:211], v[68:71]
	v_mfma_f32_16x16x32_bf16 v[64:67], v[162:165], v[208:211], v[64:67]
	s_setprio 0
	s_barrier
	v_mov_b32_e32 v128, v172
	s_add_i32 s16, s94, s86
	ds_read_b128 v[166:169], v179 offset:16384
	ds_read_b128 v[184:187], v179 offset:17408
	ds_read_b128 v[188:191], v179 offset:18432
	ds_read_b128 v[192:195], v179 offset:19456
	ds_read_b128 v[196:199], v179 offset:20480
	ds_read_b128 v[200:203], v179 offset:21504
	ds_read_b128 v[204:207], v179 offset:22528
	ds_read_b128 v[208:211], v179 offset:23552
	s_waitcnt vmcnt(2)
	s_waitcnt lgkmcnt(0)
	s_barrier
	s_setprio 1
	s_waitcnt lgkmcnt(0)
	v_mfma_f32_16x16x32_bf16 v[60:63], v[134:137], v[166:169], v[60:63]
	v_mfma_f32_16x16x32_bf16 v[56:59], v[142:145], v[166:169], v[56:59]
	v_mfma_f32_16x16x32_bf16 v[44:47], v[134:137], v[188:191], v[44:47]
	v_mfma_f32_16x16x32_bf16 v[40:43], v[142:145], v[188:191], v[40:43]
	s_mov_b32 m0, s16
	s_nop 0
	global_load_lds_dwordx4 v128, s[38:39]
	v_mfma_f32_16x16x32_bf16 v[28:31], v[134:137], v[196:199], v[28:31]
	v_mfma_f32_16x16x32_bf16 v[24:27], v[142:145], v[196:199], v[24:27]
	v_mfma_f32_16x16x32_bf16 v[12:15], v[134:137], v[204:207], v[12:15]
	v_mfma_f32_16x16x32_bf16 v[8:11], v[142:145], v[204:207], v[8:11]
	v_mfma_f32_16x16x32_bf16 v[60:63], v[138:141], v[184:187], v[60:63]
	v_mov_b32_e32 v128, v173
	s_add_i32 m0, s16, 0x2000
	s_add_u32 s50, s38, 0x100000
	global_load_lds_dwordx4 v128, s[38:39]
	v_mfma_f32_16x16x32_bf16 v[56:59], v[146:149], v[184:187], v[56:59]
	v_mfma_f32_16x16x32_bf16 v[44:47], v[138:141], v[192:195], v[44:47]
	v_mfma_f32_16x16x32_bf16 v[40:43], v[146:149], v[192:195], v[40:43]
	v_mfma_f32_16x16x32_bf16 v[28:31], v[138:141], v[200:203], v[28:31]
	s_addc_u32 s51, s39, 0
	v_mov_b32_e32 v128, v172
	s_add_i32 s16, s95, s86
	s_mov_b32 m0, s16
	s_nop 0
	global_load_lds_dwordx4 v128, s[50:51]
	v_mfma_f32_16x16x32_bf16 v[24:27], v[146:149], v[200:203], v[24:27]
	v_mfma_f32_16x16x32_bf16 v[12:15], v[138:141], v[208:211], v[12:15]
	v_mfma_f32_16x16x32_bf16 v[8:11], v[146:149], v[208:211], v[8:11]
	s_setprio 0
	s_setprio 1
	v_mfma_f32_16x16x32_bf16 v[52:55], v[150:153], v[166:169], v[52:55]
	v_mfma_f32_16x16x32_bf16 v[48:51], v[158:161], v[166:169], v[48:51]
	v_mov_b32_e32 v128, v173
	s_add_i32 m0, s16, 0x2000
	s_nop 0
	global_load_lds_dwordx4 v128, s[50:51]
	v_mfma_f32_16x16x32_bf16 v[36:39], v[150:153], v[188:191], v[36:39]
	v_mfma_f32_16x16x32_bf16 v[32:35], v[158:161], v[188:191], v[32:35]
	v_mfma_f32_16x16x32_bf16 v[20:23], v[150:153], v[196:199], v[20:23]
	v_mfma_f32_16x16x32_bf16 v[16:19], v[158:161], v[196:199], v[16:19]
	v_mov_b32_e32 v128, v172
	s_mov_b32 m0, s87
	s_nop 0
	global_load_lds_dwordx4 v128, s[34:35]
	v_mfma_f32_16x16x32_bf16 v[4:7], v[150:153], v[204:207], v[4:7]
	v_mfma_f32_16x16x32_bf16 v[0:3], v[158:161], v[204:207], v[0:3]
	v_mfma_f32_16x16x32_bf16 v[52:55], v[154:157], v[184:187], v[52:55]
	v_mfma_f32_16x16x32_bf16 v[48:51], v[162:165], v[184:187], v[48:51]
	v_mfma_f32_16x16x32_bf16 v[36:39], v[154:157], v[192:195], v[36:39]
	v_mov_b32_e32 v128, v173
	s_mov_b32 m0, s88
	s_nop 0
	global_load_lds_dwordx4 v128, s[34:35]
	v_mfma_f32_16x16x32_bf16 v[32:35], v[162:165], v[192:195], v[32:35]
	v_mfma_f32_16x16x32_bf16 v[20:23], v[154:157], v[200:203], v[20:23]
	v_mfma_f32_16x16x32_bf16 v[16:19], v[162:165], v[200:203], v[16:19]
	v_mfma_f32_16x16x32_bf16 v[4:7], v[154:157], v[208:211], v[4:7]
	v_mfma_f32_16x16x32_bf16 v[0:3], v[162:165], v[208:211], v[0:3]
	s_setprio 0
	s_barrier
; #define PG8_LDA(dst, b, h) do { if constexpr (FP8) { _Pragma("unroll") for (int m = 0; m < 4; ++m) dst##8[m] = PG8_LD8(PG8_SA(b, h), aoff, aoff1, m); } \
;         else { _Pragma("unroll") for (int m = 0; m < 4; ++m) _Pragma("unroll") for (int k = 0; k < 2; ++k) dst[m][k] = *(const LAS bf16x8*)(lds + PG8_SA(b, h) + (k ? aoff1 : aoff) + m * 2048); } } while (0)
; #define PG8_LDB(dst, b, h) do { if constexpr (FP8) { dst##8[0] = PG8_LD8(PG8_SB(b, h), boff, boff1, 0); dst##8[1] = PG8_LD8(PG8_SB(b, h), boff, boff1, 1); } \
;         else { _Pragma("unroll") for (int n = 0; n < 2; ++n) _Pragma("unroll") for (int k = 0; k < 2; ++k) dst[n][k] = *(const LAS bf16x8*)(lds + PG8_SB(b, h) + (k ? boff1 : boff) + n * 2048); } } while (0)
; #define PG8_WAIT_V(n) asm volatile("s_waitcnt vmcnt(" #n ")" ::: "memory")
; #define PG8_WAIT_L(n) asm volatile("s_waitcnt lgkmcnt(" #n ")" ::: "memory")
; #define PG8_BAR __builtin_amdgcn_s_barrier()
; #define PG8_SCHED __builtin_amdgcn_sched_barrier(0)
; #define PG8_S3 PG8_STAGE(PG8_SA(0, 1), a2 + hstepA, voffA)
; #define PG8_S4 do { PG8_STAGE(PG8_SB(1, 0), b3, voffB); PG8_STAGE(PG8_SB(1, 1), b3 + hstepB, voffB); PG8_STAGE(PG8_SA(1, 0), a3, voffA); } while (0)
; template <class Epi, class SchedT, bool ALIGN_EPI, bool SP2, bool FP8 = false>
; __device__ __forceinline__ void gemm_phase(LAS unsigned char* lds, const Gemm g, const SchedT& S, const Epi& E, const int wid) {
;     ...
;             PG8_LDB(B0, 1, 0); PG8_LDB(B1, 1, 1); PG8_SCHED; PG8_LDA(At, 1, 0); PG8_S3;
;             PG8_WAIT_V(8); PG8_WAIT_L(0); PG8_BAR; PG8_MMAP(0, 1, 0); PG8_BAR; PG8_SCHED;
;             PG8_LDA(At, 1, 1); PG8_S4;
;             PG8_WAIT_V(8); PG8_WAIT_L(0); PG8_BAR; PG8_MMAP(1, 1, 1); PG8_BAR; PG8_SCHED;
	s_add_i32 s16, 0, 0x18000
	v_add_u32_e32 v128, s16, v174
	s_add_i32 s17, 0, 0x1c000
	ds_read_b128 v[134:137], v128
	ds_read_b128 v[138:141], v128 offset:1024
	ds_read_b128 v[142:145], v180
	ds_read_b128 v[146:149], v180 offset:1024
	v_add_u32_e32 v128, s17, v174
	ds_read_b128 v[150:153], v128
	ds_read_b128 v[154:157], v128 offset:1024
	ds_read_b128 v[158:161], v181
	ds_read_b128 v[162:165], v181 offset:1024
	s_add_u32 s50, s34, 0x100000
	v_mov_b32_e32 v128, v172
	s_mov_b32 m0, s89
	ds_read_b128 v[166:169], v179 offset:32768
	ds_read_b128 v[184:187], v179 offset:33792
	ds_read_b128 v[188:191], v179 offset:34816
	ds_read_b128 v[192:195], v179 offset:35840
	ds_read_b128 v[196:199], v179 offset:36864
	ds_read_b128 v[200:203], v179 offset:37888
	ds_read_b128 v[204:207], v179 offset:38912
	ds_read_b128 v[208:211], v179 offset:39936
	s_waitcnt vmcnt(6)
	s_waitcnt lgkmcnt(0)
	s_barrier
	s_setprio 1
	s_waitcnt lgkmcnt(0)
	v_mfma_f32_16x16x32_bf16 v[124:127], v[134:137], v[166:169], v[124:127]
	v_mfma_f32_16x16x32_bf16 v[120:123], v[142:145], v[166:169], v[120:123]
	v_mfma_f32_16x16x32_bf16 v[108:111], v[134:137], v[188:191], v[108:111]
	v_mfma_f32_16x16x32_bf16 v[104:107], v[142:145], v[188:191], v[104:107]
	v_mfma_f32_16x16x32_bf16 v[92:95], v[134:137], v[196:199], v[92:95]
	v_mfma_f32_16x16x32_bf16 v[88:91], v[142:145], v[196:199], v[88:91]
	v_mfma_f32_16x16x32_bf16 v[76:79], v[134:137], v[204:207], v[76:79]
	v_mfma_f32_16x16x32_bf16 v[72:75], v[142:145], v[204:207], v[72:75]
	v_mfma_f32_16x16x32_bf16 v[124:127], v[138:141], v[184:187], v[124:127]
	v_mfma_f32_16x16x32_bf16 v[120:123], v[146:149], v[184:187], v[120:123]
	s_addc_u32 s51, s35, 0
	s_nop 0
	global_load_lds_dwordx4 v128, s[50:51]
	v_mfma_f32_16x16x32_bf16 v[108:111], v[138:141], v[192:195], v[108:111]
	v_mfma_f32_16x16x32_bf16 v[104:107], v[146:149], v[192:195], v[104:107]
	v_mfma_f32_16x16x32_bf16 v[92:95], v[138:141], v[200:203], v[92:95]
	v_mfma_f32_16x16x32_bf16 v[88:91], v[146:149], v[200:203], v[88:91]
	v_mfma_f32_16x16x32_bf16 v[76:79], v[138:141], v[208:211], v[76:79]
	v_mfma_f32_16x16x32_bf16 v[72:75], v[146:149], v[208:211], v[72:75]
	s_setprio 0
	s_setprio 1
	v_mfma_f32_16x16x32_bf16 v[116:119], v[150:153], v[166:169], v[116:119]
	v_mfma_f32_16x16x32_bf16 v[112:115], v[158:161], v[166:169], v[112:115]
	v_mfma_f32_16x16x32_bf16 v[100:103], v[150:153], v[188:191], v[100:103]
	v_mfma_f32_16x16x32_bf16 v[96:99], v[158:161], v[188:191], v[96:99]
	v_mfma_f32_16x16x32_bf16 v[84:87], v[150:153], v[196:199], v[84:87]
	v_mov_b32_e32 v128, v173
	s_mov_b32 m0, s90
	s_nop 0
	global_load_lds_dwordx4 v128, s[50:51]
	v_mfma_f32_16x16x32_bf16 v[80:83], v[158:161], v[196:199], v[80:83]
	v_mfma_f32_16x16x32_bf16 v[68:71], v[150:153], v[204:207], v[68:71]
	v_mfma_f32_16x16x32_bf16 v[64:67], v[158:161], v[204:207], v[64:67]
	v_mfma_f32_16x16x32_bf16 v[116:119], v[154:157], v[184:187], v[116:119]
	v_mfma_f32_16x16x32_bf16 v[112:115], v[162:165], v[184:187], v[112:115]
	v_mfma_f32_16x16x32_bf16 v[100:103], v[154:157], v[192:195], v[100:103]
	v_mfma_f32_16x16x32_bf16 v[96:99], v[162:165], v[192:195], v[96:99]
	v_mfma_f32_16x16x32_bf16 v[84:87], v[154:157], v[200:203], v[84:87]
	v_mfma_f32_16x16x32_bf16 v[80:83], v[162:165], v[200:203], v[80:83]
	v_mfma_f32_16x16x32_bf16 v[68:71], v[154:157], v[208:211], v[68:71]
	v_mfma_f32_16x16x32_bf16 v[64:67], v[162:165], v[208:211], v[64:67]
	s_setprio 0
	s_barrier
	v_mov_b32_e32 v128, v172
	ds_read_b128 v[166:169], v179 offset:49152
	ds_read_b128 v[184:187], v179 offset:50176
	ds_read_b128 v[188:191], v179 offset:51200
	ds_read_b128 v[192:195], v179 offset:52224
	ds_read_b128 v[196:199], v179 offset:53248
	ds_read_b128 v[200:203], v179 offset:54272
	ds_read_b128 v[204:207], v179 offset:55296
	ds_read_b128 v[208:211], v179 offset:56320
	s_waitcnt vmcnt(2)
	s_waitcnt lgkmcnt(0)
	s_barrier
; #define PG8_LDA(dst, b, h) do { if constexpr (FP8) { _Pragma("unroll") for (int m = 0; m < 4; ++m) dst##8[m] = PG8_LD8(PG8_SA(b, h), aoff, aoff1, m); } \
;         else { _Pragma("unroll") for (int m = 0; m < 4; ++m) _Pragma("unroll") for (int k = 0; k < 2; ++k) dst[m][k] = *(const LAS bf16x8*)(lds + PG8_SA(b, h) + (k ? aoff1 : aoff) + m * 2048); } } while (0)
; #define PG8_LDB(dst, b, h) do { if constexpr (FP8) { dst##8[0] = PG8_LD8(PG8_SB(b, h), boff, boff1, 0); dst##8[1] = PG8_LD8(PG8_SB(b, h), boff, boff1, 1); } \
;         else { _Pragma("unroll") for (int n = 0; n < 2; ++n) _Pragma("unroll") for (int k = 0; k < 2; ++k) dst[n][k] = *(const LAS bf16x8*)(lds + PG8_SB(b, h) + (k ? boff1 : boff) + n * 2048); } } while (0)
; #define PG8_WAIT_V(n) asm volatile("s_waitcnt vmcnt(" #n ")" ::: "memory")
; #define PG8_WAIT_L(n) asm volatile("s_waitcnt lgkmcnt(" #n ")" ::: "memory")
; #define PG8_BAR __builtin_amdgcn_s_barrier()
; #define PG8_SCHED __builtin_amdgcn_sched_barrier(0)
; #define PG8_S3 PG8_STAGE(PG8_SA(0, 1), a2 + hstepA, voffA)
; #define PG8_S4 do { PG8_STAGE(PG8_SB(1, 0), b3, voffB); PG8_STAGE(PG8_SB(1, 1), b3 + hstepB, voffB); PG8_STAGE(PG8_SA(1, 0), a3, voffA); } while (0)
; template <class Epi, class SchedT, bool ALIGN_EPI, bool SP2, bool FP8 = false>
; __device__ __forceinline__ void gemm_phase(LAS unsigned char* lds, const Gemm g, const SchedT& S, const Epi& E, const int wid) {
;     ...
;             PG8_LDB(B0, 1, 0); PG8_LDB(B1, 1, 1); PG8_SCHED; PG8_LDA(At, 1, 0); PG8_S3;
;             PG8_WAIT_V(8); PG8_WAIT_L(0); PG8_BAR; PG8_MMAP(0, 1, 0); PG8_BAR; PG8_SCHED;
;             PG8_LDA(At, 1, 1); PG8_S4;
;             PG8_WAIT_V(8); PG8_WAIT_L(0); PG8_BAR; PG8_MMAP(1, 1, 1); PG8_BAR; PG8_SCHED;
;     ...
;         if constexpr (ALIGN_EPI) { if (wr == 0) PG8_BAR; }
	s_setprio 1
	s_waitcnt lgkmcnt(0)
	v_mfma_f32_16x16x32_bf16 v[60:63], v[134:137], v[166:169], v[60:63]
	v_mfma_f32_16x16x32_bf16 v[56:59], v[142:145], v[166:169], v[56:59]
	v_mfma_f32_16x16x32_bf16 v[44:47], v[134:137], v[188:191], v[44:47]
	v_mfma_f32_16x16x32_bf16 v[40:43], v[142:145], v[188:191], v[40:43]
	s_add_i32 s16, s16, s86
	v_lshl_add_u64 v[170:171], s[38:39], 0, v[128:129]
	v_lshl_add_u64 v[170:171], v[170:171], 0, s[8:9]
	s_mov_b32 m0, s16
	v_mov_b32_e32 v128, v173
	global_load_lds_dwordx4 v[170:171], off
	v_mfma_f32_16x16x32_bf16 v[28:31], v[134:137], v[196:199], v[28:31]
	v_mfma_f32_16x16x32_bf16 v[24:27], v[142:145], v[196:199], v[24:27]
	v_mfma_f32_16x16x32_bf16 v[12:15], v[134:137], v[204:207], v[12:15]
	v_mfma_f32_16x16x32_bf16 v[8:11], v[142:145], v[204:207], v[8:11]
	v_mfma_f32_16x16x32_bf16 v[60:63], v[138:141], v[184:187], v[60:63]
	s_add_i32 m0, s16, 0x2000
	s_nop 0
	v_lshl_add_u64 v[170:171], s[38:39], 0, v[128:129]
	s_add_u32 s38, s38, 0x100080
	v_lshl_add_u64 v[170:171], v[170:171], 0, s[8:9]
	s_addc_u32 s39, s39, 0
	v_mov_b32_e32 v128, v172
	s_add_i32 s16, s17, s86
	global_load_lds_dwordx4 v[170:171], off
	v_mfma_f32_16x16x32_bf16 v[56:59], v[146:149], v[184:187], v[56:59]
	v_mfma_f32_16x16x32_bf16 v[44:47], v[138:141], v[192:195], v[44:47]
	v_mfma_f32_16x16x32_bf16 v[40:43], v[146:149], v[192:195], v[40:43]
	v_mfma_f32_16x16x32_bf16 v[28:31], v[138:141], v[200:203], v[28:31]
	s_mov_b32 m0, s16
	s_nop 0
	global_load_lds_dwordx4 v128, s[38:39]
	v_mfma_f32_16x16x32_bf16 v[24:27], v[146:149], v[200:203], v[24:27]
	v_mfma_f32_16x16x32_bf16 v[12:15], v[138:141], v[208:211], v[12:15]
	v_mfma_f32_16x16x32_bf16 v[8:11], v[146:149], v[208:211], v[8:11]
	s_setprio 0
	s_setprio 1
	v_mfma_f32_16x16x32_bf16 v[52:55], v[150:153], v[166:169], v[52:55]
	v_mfma_f32_16x16x32_bf16 v[48:51], v[158:161], v[166:169], v[48:51]
	v_mov_b32_e32 v128, v173
	s_add_i32 m0, s16, 0x2000
	s_nop 0
	global_load_lds_dwordx4 v128, s[38:39]
	v_mfma_f32_16x16x32_bf16 v[36:39], v[150:153], v[188:191], v[36:39]
	v_mfma_f32_16x16x32_bf16 v[32:35], v[158:161], v[188:191], v[32:35]
	v_mfma_f32_16x16x32_bf16 v[20:23], v[150:153], v[196:199], v[20:23]
	v_mfma_f32_16x16x32_bf16 v[16:19], v[158:161], v[196:199], v[16:19]
	v_mov_b32_e32 v128, v172
	s_mov_b32 m0, s92
	v_lshl_add_u64 v[170:171], s[34:35], 0, v[128:129]
	v_lshl_add_u64 v[170:171], v[170:171], 0, s[8:9]
	v_mov_b32_e32 v128, v173
	global_load_lds_dwordx4 v[170:171], off
	v_mfma_f32_16x16x32_bf16 v[4:7], v[150:153], v[204:207], v[4:7]
	v_mfma_f32_16x16x32_bf16 v[0:3], v[158:161], v[204:207], v[0:3]
	v_mfma_f32_16x16x32_bf16 v[52:55], v[154:157], v[184:187], v[52:55]
	v_mfma_f32_16x16x32_bf16 v[48:51], v[162:165], v[184:187], v[48:51]
	v_mfma_f32_16x16x32_bf16 v[36:39], v[154:157], v[192:195], v[36:39]
	s_mov_b32 m0, s93
	v_lshl_add_u64 v[170:171], s[34:35], 0, v[128:129]
	v_lshl_add_u64 v[170:171], v[170:171], 0, s[8:9]
	global_load_lds_dwordx4 v[170:171], off
	v_mfma_f32_16x16x32_bf16 v[32:35], v[162:165], v[192:195], v[32:35]
	v_mfma_f32_16x16x32_bf16 v[20:23], v[154:157], v[200:203], v[20:23]
	v_mfma_f32_16x16x32_bf16 v[16:19], v[162:165], v[200:203], v[16:19]
	v_mfma_f32_16x16x32_bf16 v[4:7], v[154:157], v[208:211], v[4:7]
	v_mfma_f32_16x16x32_bf16 v[0:3], v[162:165], v[208:211], v[0:3]
	s_setprio 0
	s_barrier
	s_add_u32 s24, s24, 0x100
	s_addc_u32 s25, s25, 0
	s_add_u32 s46, s46, 0x100
	s_addc_u32 s47, s47, 0
	s_cmp_ge_i32 s48, s30
	s_mov_b32 s34, s48
	s_cbranch_scc0 .LBB0_970
	s_and_b64 vcc, exec, s[96:97]
	s_cbranch_vccz .LBB0_973
